# split grid barrier at the two conversion sites: arrive (and release by the XCD's last arriver) first, then the dynamic weight conversion, then poll/acquire
# speedup vs baseline: 1.0100x; 1.0043x over previous
.Lmy_sb_arrived:
	v_readfirstlane_b32 s30, v2
	v_readfirstlane_b32 s31, v0
.Lmy_sb_mid:
	s_or_b64 exec, exec, s[4:5]
	s_cmp_gt_u32 s40, 5
	s_cbranch_scc1 .Lmy_cvm_skip
	v_mov_b32_e32 v37, v237
	v_readlane_b32 s6, v254, 0
	v_readfirstlane_b32 s5, v37
	s_ashr_i32 s5, s5, 6
	s_add_i32 s12, s5, s6
	s_mov_b32 s101, s12
	v_readfirstlane_b32 s100, v237
	s_cmp_gt_u32 s100, 63
	s_cbranch_scc1 .Lmy_cv5_w
	s_mov_b64 s[44:45], exec
	s_mov_b64 exec, 1
	s_lshl_b32 s100, s40, 8
	s_add_i32 s100, s100, 0x5000
	v_mov_b32_e32 v90, s100
	v_mov_b32_e32 v91, 1
	global_atomic_add v91, v90, v91, s[36:37] sc0
	v_mov_b32_e32 v90, 0x21008
	s_waitcnt vmcnt(0)
	ds_write_b32 v90, v91
	s_waitcnt lgkmcnt(0)
	s_mov_b64 exec, s[44:45]

.Lmy_cvm_skip:
	s_and_saveexec_b64 s[4:5], s[74:75]
	s_cbranch_execz .LBB0_541
	v_mov_b32_e32 v2, s30
	v_mov_b32_e32 v0, s31

.LBB0_854:
	s_getreg_b32 s6, hwreg(HW_REG_XCC_ID, 0, 4)
	s_waitcnt vmcnt(0)
	s_waitcnt vmcnt(0)
	s_barrier
	s_and_saveexec_b64 s[4:5], s[74:75]
	s_cbranch_execz .Lmy_sa_mid
	v_readlane_b32 s7, v255, 10
	v_readlane_b32 s8, v255, 11
	s_and_b32 s6, s6, 15
	s_lshl_b32 s6, s6, 8
	v_mov_b32_e32 v0, s7
	v_mov_b32_e32 v2, s8
	ds_read_b32 v3, v0
	ds_read_b32 v2, v2
	s_add_i32 s9, s6, 0x1400
	s_add_i32 s10, s6, 0x4000
	s_waitcnt vmcnt(0) lgkmcnt(0)
	v_cmp_ne_u32_e32 vcc, 0, v3
	s_cbranch_vccnz .Lmy_xb1_have
	s_mov_b32 s12, 0

.Lmy_sa_mid:
	s_or_b64 exec, exec, s[4:5]
	v_mov_b32_e32 v35, v237
	s_mul_i32 s7, s56, 0x1600000
	v_readfirstlane_b32 s4, v35
	s_ashr_i32 s19, s4, 6
	v_readlane_b32 s4, v254, 0
	v_readfirstlane_b32 s100, v237
	s_cmp_gt_u32 s100, 63
	s_cbranch_scc1 .Lmy_cv2_w
	s_mov_b64 s[44:45], exec
	s_mov_b64 exec, 1
	s_lshl_b32 s100, s40, 8
	s_add_i32 s100, s100, 0x5000
	v_mov_b32_e32 v90, s100
	v_mov_b32_e32 v91, 1
	global_atomic_add v91, v90, v91, s[36:37] sc0
	v_mov_b32_e32 v90, 0x21008
	s_waitcnt vmcnt(0)
	ds_write_b32 v90, v91
	s_waitcnt lgkmcnt(0)
	s_mov_b64 exec, s[44:45]

.Lmy_cvf_end:
	s_and_saveexec_b64 s[4:5], s[74:75]
	v_readlane_b32 s26, v254, 28
	v_readlane_b32 s57, v254, 29
	v_readlane_b32 s68, v254, 30
	v_readlane_b32 s69, v255, 7
	v_readlane_b32 s72, v255, 8
	s_mov_b32 s27, 0x600000
	s_movk_i32 s95, 0xc00
	s_cbranch_execz .LBB0_906
	v_mov_b32_e32 v2, s30
	v_mov_b32_e32 v0, s31
